# FFN rmsnorm loop: loop-top wait no longer drains the previous row's stores
# speedup vs baseline: 1.0038x; 1.0038x over previous
; template <bool GATES>
; __device__ __forceinline__ void phase_norm(const float* x, const float* gain, bf16_t* hn, int nrows, const float* w_in_l, const float* bif, float* gif, LAS unsigned char* lds) {
;     ...
;     const int gw = blockIdx.x * 8 + wave, NGW = gridDim.x * 8;
;     f32x4 gv[4];
; #pragma unroll
;     for (int j = 0; j < 4; ++j) gv[j] = *(const f32x4*)(gain + 4 * lane + 256 * j);
;     f32x4 v[4], nx[4];
;     if (gw < nrows) { const f32x4* xr = (const f32x4*)(x + (size_t)gw * DM) + lane;
; #pragma unroll
;         for (int j = 0; j < 4; ++j) nx[j] = xr[64 * j]; }
;     for (int row = gw; row < nrows; row += NGW) {
.LBB0_61:
	s_andn2_b64 vcc, exec, s[0:1]
	s_cbranch_vccnz .LBB0_68
	v_mov_b32_e32 v35, v194
	v_readlane_b32 s0, v254, 21
	v_ashrrev_i32_e32 v34, 6, v35
	s_nop 0
	v_add_u32_e32 v50, s0, v34
	v_cmp_gt_i32_e32 vcc, s51, v50
	s_and_saveexec_b64 s[4:5], vcc
	s_cbranch_execz .LBB0_67
	s_lshl_b32 s0, s64, 10
	s_ashr_i32 s1, s0, 31
	v_readlane_b32 s8, v254, 47
	v_ashrrev_i32_e32 v51, 31, v50
	s_lshl_b64 s[0:1], s[0:1], 2
	v_readlane_b32 s18, v254, 57
	v_lshlrev_b32_e32 v0, 4, v35
	v_lshlrev_b64 v[18:19], 12, v[50:51]
	v_readlane_b32 s19, v254, 58
	s_add_u32 s0, s18, s0
	v_and_b32_e32 v0, 0x3f0, v0
	v_lshl_add_u64 v[18:19], s[88:89], 0, v[18:19]
	s_addc_u32 s1, s19, s1
	v_lshl_add_u64 v[18:19], v[18:19], 0, v[0:1]
	global_load_dwordx4 v[2:5], v0, s[0:1]
	global_load_dwordx4 v[6:9], v0, s[0:1] offset:1024
	global_load_dwordx4 v[10:13], v0, s[0:1] offset:2048
	global_load_dwordx4 v[14:17], v0, s[0:1] offset:3072
	global_load_dwordx4 v[30:33], v[18:19], off
	global_load_dwordx4 v[26:29], v[18:19], off offset:1024
	global_load_dwordx4 v[22:25], v[18:19], off offset:2048
	s_nop 0
	global_load_dwordx4 v[18:21], v[18:19], off offset:3072
	v_and_b32_e32 v36, 64, v235
	v_add_u32_e32 v36, 64, v36
	v_xor_b32_e32 v37, 1, v235
	v_cmp_lt_i32_e32 vcc, v37, v36
	v_lshlrev_b64 v[38:39], 7, v[50:51]
	v_readlane_b32 s0, v254, 22
	v_cndmask_b32_e32 v37, v235, v37, vcc
	v_lshlrev_b32_e32 v56, 2, v37
	v_xor_b32_e32 v37, 2, v235
	v_cmp_lt_i32_e32 vcc, v37, v36
	v_add_u32_e32 v34, s0, v34
	s_mov_b64 s[6:7], 0
	v_cndmask_b32_e32 v37, v235, v37, vcc
	v_lshlrev_b32_e32 v57, 2, v37
	v_xor_b32_e32 v37, 4, v235
	v_cmp_lt_i32_e32 vcc, v37, v36
	v_readlane_b32 s9, v254, 48
	v_readlane_b32 s10, v254, 49
	v_cndmask_b32_e32 v37, v235, v37, vcc
	v_lshlrev_b32_e32 v58, 2, v37
	v_xor_b32_e32 v37, 8, v235
	v_cmp_lt_i32_e32 vcc, v37, v36
	v_readlane_b32 s11, v254, 50
	v_readlane_b32 s12, v254, 51
	v_cndmask_b32_e32 v37, v235, v37, vcc
	v_lshlrev_b32_e32 v59, 2, v37
	v_xor_b32_e32 v37, 16, v235
	v_cmp_lt_i32_e32 vcc, v37, v36
	v_readlane_b32 s13, v254, 52
	v_readlane_b32 s14, v254, 53
	v_cndmask_b32_e32 v37, v235, v37, vcc
	v_lshlrev_b32_e32 v60, 2, v37
	v_xor_b32_e32 v37, 32, v235
	v_cmp_lt_i32_e32 vcc, v37, v36
	v_readlane_b32 s15, v254, 54
	v_readlane_b32 s16, v254, 55
	v_cndmask_b32_e32 v36, v235, v37, vcc
	v_lshlrev_b32_e32 v61, 2, v36
	v_lshlrev_b32_e32 v36, 18, v35
	v_and_b32_e32 v36, 0xc00000, v36
	v_mov_b32_e32 v37, v1
	v_lshl_add_u64 v[36:37], v[36:37], 0, v[38:39]
	v_and_b32_e32 v35, 15, v35
	v_lshl_or_b32 v36, v35, 3, v36
	v_ashrrev_i32_e32 v35, 31, v34
	v_lshlrev_b64 v[34:35], 12, v[34:35]
	v_or_b32_e32 v34, v34, v0
	v_lshl_add_u64 v[52:53], s[72:73], 0, v[36:37]
	v_lshl_add_u64 v[54:55], s[88:89], 0, v[34:35]
	v_readlane_b32 s17, v254, 56
	v_readlane_b32 s20, v254, 59
	v_readlane_b32 s21, v254, 60
	v_readlane_b32 s22, v254, 61
	v_readlane_b32 s23, v254, 62
	s_waitcnt vmcnt(0)
	s_branch .LBB0_65

; template <bool GATES>
; __device__ __forceinline__ void phase_norm(const float* x, const float* gain, bf16_t* hn, int nrows, const float* w_in_l, const float* bif, float* gif, LAS unsigned char* lds) {
;     ...
;     for (int row = gw; row < nrows; row += NGW) {
;         float ss = 0.f;
; #pragma unroll
;         for (int j = 0; j < 4; ++j) v[j] = nx[j];
;         if (row + NGW < nrows) { const f32x4* xr = (const f32x4*)(x + (size_t)(row + NGW) * DM) + lane;
; #pragma unroll
;             for (int j = 0; j < 4; ++j) nx[j] = xr[64 * j]; }
.LBB0_65:
	v_add_u32_e32 v50, s52, v50
	v_cmp_gt_i32_e64 s[0:1], s51, v50
	v_cmp_lt_i32_e32 vcc, s49, v50
	s_waitcnt vmcnt(4)
	v_mov_b32_e32 v34, v30
	v_mov_b32_e32 v35, v31
	v_mov_b32_e32 v36, v32
	v_mov_b32_e32 v37, v33
	v_mov_b32_e32 v38, v26
	v_mov_b32_e32 v39, v27
	v_mov_b32_e32 v40, v28
	v_mov_b32_e32 v41, v29
	v_mov_b32_e32 v42, v22
	v_mov_b32_e32 v43, v23
	v_mov_b32_e32 v44, v24
	v_mov_b32_e32 v45, v25
	v_mov_b32_e32 v46, v18
	v_mov_b32_e32 v47, v19
	v_mov_b32_e32 v48, v20
	v_mov_b32_e32 v49, v21
	s_and_saveexec_b64 s[8:9], s[0:1]
	s_cbranch_execz .LBB0_64
	global_load_dwordx4 v[34:37], v[54:55], off
	global_load_dwordx4 v[38:41], v[54:55], off offset:1024
	global_load_dwordx4 v[42:45], v[54:55], off offset:2048
	global_load_dwordx4 v[46:49], v[54:55], off offset:3072
	s_branch .LBB0_64
